# attention KV loops: row-max as four independent chains instead of one serial chain
# baseline (speedup 1.0000x reference)
; DI float half_swap_max(float x) { const unsigned u = __float_as_uint(x); const auto r = __builtin_amdgcn_permlane32_swap(u, u, false, false); return fmaxf(__uint_as_float(r[0]), __uint_as_float(r[1])); }
; #define MFMA32(a, b, c) __builtin_amdgcn_mfma_f32_32x32x16_bf16((a), (b), (c), 0, 0, 0)
; template <int DQK, int MODE>
; DI void attn_phase(const bf16_t* __restrict__ QK, int ldq, const bf16_t* __restrict__ Vt, int VC, bf16_t* __restrict__ O, int ldo, int nhu, bool skip_ctx, const float* __restrict__ qgain, const f32x2* __restrict__ rope, float qscale, char* shm) {
;     ...
;         for (int kt = 0; kt < nkt; ++kt) {
;             const char* Kc = Kl + (kt & 1) * BUFB; const char* Vc = Vl + (kt & 1) * BUFB;
;             if (kt + 1 < nkt) ATT_LOAD(kt + 1);
;             f32x16 st0, st1;
; #pragma unroll
;             for (int i = 0; i < 16; ++i) { st0[i] = 0.f; st1[i] = 0.f; }
; #pragma unroll
;             for (int ks = 0; ks < DQK / 16; ++ks) {
;                 const bf16x8 a0 = *(const bf16x8*)(Kc + r * KS + ks * 32 + h * 16), a1 = *(const bf16x8*)(Kc + (32 + r) * KS + ks * 32 + h * 16);
;                 st0 = MFMA32(a0, qf[ks], st0); st1 = MFMA32(a1, qf[ks], st1);
;             }
;             float mx = st0[0];
; #pragma unroll
;             for (int i = 0; i < 16; ++i) mx = __builtin_fmaxf(__builtin_fmaxf(mx, st0[i]), st1[i]);
;             mx = half_swap_max(mx);
;             if (__any(mx > mrun + 8.f)) {
;                 const float mnew = fmaxf(mrun, mx), alpha = __builtin_amdgcn_exp2f(mrun - mnew); mrun = mnew; lsum *= alpha;
; #pragma unroll
;                 for (int t = 0; t < 4; ++t)
; #pragma unroll
;                     for (int i = 0; i < 16; ++i) oacc[t][i] *= alpha;
;             }
.LBB0_1328:
	s_and_b32 s0, 1, s10
	s_cselect_b32 s1, 0, 0x6c00
	v_add_u32_e32 v120, s1, v162
	ds_read_b128 v[64:67], v120
	ds_read_b128 v[112:115], v120 offset:32
	s_waitcnt lgkmcnt(1)
	v_mfma_f32_32x32x16_bf16 v[80:95], v[64:67], v[104:107], 0
	ds_read_b128 v[64:67], v120 offset:4608
	ds_read_b128 v[116:119], v120 offset:4640
	s_waitcnt lgkmcnt(1)
	v_mfma_f32_32x32x16_bf16 v[64:79], v[64:67], v[104:107], 0
	v_mfma_f32_32x32x16_bf16 v[80:95], v[112:115], v[108:111], v[80:95]
	ds_read_b128 v[112:115], v120 offset:64
	ds_read_b128 v[168:171], v120 offset:96
	s_waitcnt lgkmcnt(2)
	v_mfma_f32_32x32x16_bf16 v[64:79], v[116:119], v[108:111], v[64:79]
	s_waitcnt lgkmcnt(1)
	v_mfma_f32_32x32x16_bf16 v[80:95], v[112:115], v[96:99], v[80:95]
	ds_read_b128 v[112:115], v120 offset:4672
	ds_read_b128 v[172:175], v120 offset:4704
	global_load_dwordx4 v[120:123], v[154:155], off
	global_load_dwordx4 v[116:119], v[150:151], off
	s_waitcnt lgkmcnt(1)
	v_mfma_f32_32x32x16_bf16 v[64:79], v[112:115], v[96:99], v[64:79]
	global_load_dwordx4 v[112:115], v[152:153], off
	s_waitcnt lgkmcnt(0)
	v_mfma_f32_32x32x16_bf16 v[64:79], v[172:175], v[100:103], v[64:79]
	v_mfma_f32_32x32x16_bf16 v[80:95], v[168:171], v[100:103], v[80:95]
	s_nop 10
	v_max3_f32 v167, v64, v65, v66
	v_max3_f32 v168, v67, v68, v69
	v_max3_f32 v169, v70, v71, v72
	v_max3_f32 v170, v73, v74, v75
	v_max3_f32 v167, v167, v76, v77
	v_max3_f32 v168, v168, v78, v79
	v_max3_f32 v169, v169, v80, v81
	v_max3_f32 v170, v170, v82, v83
	v_max3_f32 v167, v167, v84, v85
	v_max3_f32 v168, v168, v86, v87
	v_max3_f32 v169, v169, v88, v89
	v_max3_f32 v170, v170, v90, v91
	v_max3_f32 v167, v167, v92, v93
	v_max3_f32 v168, v168, v94, v95
	v_max3_f32 v167, v167, v168, v169
	v_max_f32_e32 v167, v167, v170
	v_mov_b32_e32 v168, v167
	s_nop 1
	v_permlane32_swap_b32_e32 v167, v168
	v_max_f32_e32 v168, v168, v168
	v_max_f32_e32 v167, v167, v167
	v_max_f32_e32 v167, v167, v168
	v_add_f32_e32 v168, 0x41000000, v156
	v_cmp_gt_f32_e32 vcc, v167, v168
	s_cbranch_vccz .LBB0_1327
	v_max_f32_e32 v167, v167, v167
	v_max_f32_e32 v168, v156, v156
	v_max_f32_e32 v167, v168, v167
	v_sub_f32_e32 v156, v156, v167
	v_exp_f32_e32 v156, v156
	s_nop 0
	v_pk_mul_f32 v[62:63], v[62:63], v[156:157] op_sel_hi:[1,0]
	v_pk_mul_f32 v[60:61], v[60:61], v[156:157] op_sel_hi:[1,0]
	v_pk_mul_f32 v[58:59], v[58:59], v[156:157] op_sel_hi:[1,0]
	v_pk_mul_f32 v[56:57], v[56:57], v[156:157] op_sel_hi:[1,0]
	v_pk_mul_f32 v[54:55], v[54:55], v[156:157] op_sel_hi:[1,0]
	v_pk_mul_f32 v[52:53], v[52:53], v[156:157] op_sel_hi:[1,0]
	v_pk_mul_f32 v[50:51], v[50:51], v[156:157] op_sel_hi:[1,0]
	v_pk_mul_f32 v[48:49], v[48:49], v[156:157] op_sel_hi:[1,0]
	v_pk_mul_f32 v[46:47], v[46:47], v[156:157] op_sel_hi:[1,0]
	v_pk_mul_f32 v[44:45], v[44:45], v[156:157] op_sel_hi:[1,0]
	v_pk_mul_f32 v[42:43], v[42:43], v[156:157] op_sel_hi:[1,0]
	v_pk_mul_f32 v[40:41], v[40:41], v[156:157] op_sel_hi:[1,0]
	v_pk_mul_f32 v[38:39], v[38:39], v[156:157] op_sel_hi:[1,0]
	v_pk_mul_f32 v[36:37], v[36:37], v[156:157] op_sel_hi:[1,0]
	v_pk_mul_f32 v[34:35], v[34:35], v[156:157] op_sel_hi:[1,0]
	v_pk_mul_f32 v[32:33], v[32:33], v[156:157] op_sel_hi:[1,0]
	v_pk_mul_f32 v[30:31], v[30:31], v[156:157] op_sel_hi:[1,0]
	v_pk_mul_f32 v[28:29], v[28:29], v[156:157] op_sel_hi:[1,0]
	v_pk_mul_f32 v[26:27], v[26:27], v[156:157] op_sel_hi:[1,0]
	v_pk_mul_f32 v[24:25], v[24:25], v[156:157] op_sel_hi:[1,0]
	v_pk_mul_f32 v[22:23], v[22:23], v[156:157] op_sel_hi:[1,0]
	v_pk_mul_f32 v[20:21], v[20:21], v[156:157] op_sel_hi:[1,0]
	v_pk_mul_f32 v[18:19], v[18:19], v[156:157] op_sel_hi:[1,0]
	v_pk_mul_f32 v[16:17], v[16:17], v[156:157] op_sel_hi:[1,0]
	v_pk_mul_f32 v[14:15], v[14:15], v[156:157] op_sel_hi:[1,0]
	v_pk_mul_f32 v[12:13], v[12:13], v[156:157] op_sel_hi:[1,0]
	v_pk_mul_f32 v[10:11], v[10:11], v[156:157] op_sel_hi:[1,0]
	v_pk_mul_f32 v[8:9], v[8:9], v[156:157] op_sel_hi:[1,0]
	v_pk_mul_f32 v[6:7], v[6:7], v[156:157] op_sel_hi:[1,0]
	v_pk_mul_f32 v[4:5], v[4:5], v[156:157] op_sel_hi:[1,0]
	v_pk_mul_f32 v[2:3], v[2:3], v[156:157] op_sel_hi:[1,0]
	v_pk_mul_f32 v[0:1], v[0:1], v[156:157] op_sel_hi:[1,0]
	v_mul_f32_e32 v166, v166, v156
	v_mov_b32_e32 v156, v167
	s_branch .LBB0_1327

; DI float half_swap_max(float x) { const unsigned u = __float_as_uint(x); const auto r = __builtin_amdgcn_permlane32_swap(u, u, false, false); return fmaxf(__uint_as_float(r[0]), __uint_as_float(r[1])); }
; #define MFMA32(a, b, c) __builtin_amdgcn_mfma_f32_32x32x16_bf16((a), (b), (c), 0, 0, 0)
; template <int DQK, int MODE>
; DI void attn_phase(const bf16_t* __restrict__ QK, int ldq, const bf16_t* __restrict__ Vt, int VC, bf16_t* __restrict__ O, int ldo, int nhu, bool skip_ctx, const float* __restrict__ qgain, const f32x2* __restrict__ rope, float qscale, char* shm) {
;     ...
;         for (int kt = 0; kt < nkt; ++kt) {
;             const char* Kc = Kl + (kt & 1) * BUFB; const char* Vc = Vl + (kt & 1) * BUFB;
;             if (kt + 1 < nkt) ATT_LOAD(kt + 1);
;             f32x16 st0, st1;
; #pragma unroll
;             for (int i = 0; i < 16; ++i) { st0[i] = 0.f; st1[i] = 0.f; }
; #pragma unroll
;             for (int ks = 0; ks < DQK / 16; ++ks) {
;                 const bf16x8 a0 = *(const bf16x8*)(Kc + r * KS + ks * 32 + h * 16), a1 = *(const bf16x8*)(Kc + (32 + r) * KS + ks * 32 + h * 16);
;                 st0 = MFMA32(a0, qf[ks], st0); st1 = MFMA32(a1, qf[ks], st1);
;             }
;             float mx = st0[0];
; #pragma unroll
;             for (int i = 0; i < 16; ++i) mx = __builtin_fmaxf(__builtin_fmaxf(mx, st0[i]), st1[i]);
;             mx = half_swap_max(mx);
;             if (__any(mx > mrun + 8.f)) {
;                 const float mnew = fmaxf(mrun, mx), alpha = __builtin_amdgcn_exp2f(mrun - mnew); mrun = mnew; lsum *= alpha;
; #pragma unroll
;                 for (int t = 0; t < 4; ++t)
; #pragma unroll
;                     for (int i = 0; i < 16; ++i) oacc[t][i] *= alpha;
;             }
.LBB0_3394:
	s_and_b32 s8, 1, s0
	s_cselect_b32 s9, 0, 0x8c00
	v_add_u32_e32 v140, s9, v195
	ds_read_b128 v[64:67], v140
	ds_read_b128 v[128:131], v140 offset:32
	s_waitcnt lgkmcnt(1)
	v_mfma_f32_32x32x16_bf16 v[80:95], v[64:67], v[100:103], 0
	ds_read_b128 v[64:67], v140 offset:8704
	ds_read_b128 v[132:135], v140 offset:8736
	s_waitcnt lgkmcnt(1)
	v_mfma_f32_32x32x16_bf16 v[64:79], v[64:67], v[100:103], 0
	v_mfma_f32_32x32x16_bf16 v[80:95], v[128:131], v[108:111], v[80:95]
	s_waitcnt lgkmcnt(0)
	v_mfma_f32_32x32x16_bf16 v[64:79], v[132:135], v[108:111], v[64:79]
	ds_read_b128 v[128:131], v140 offset:64
	ds_read_b128 v[132:135], v140 offset:96
	s_waitcnt lgkmcnt(1)
	v_mfma_f32_32x32x16_bf16 v[80:95], v[128:131], v[116:119], v[80:95]
	ds_read_b128 v[128:131], v140 offset:8768
	ds_read_b128 v[136:139], v140 offset:8800
	s_waitcnt lgkmcnt(1)
	v_mfma_f32_32x32x16_bf16 v[64:79], v[128:131], v[116:119], v[64:79]
	v_mfma_f32_32x32x16_bf16 v[80:95], v[132:135], v[124:127], v[80:95]
	ds_read_b128 v[128:131], v140 offset:128
	ds_read_b128 v[132:135], v140 offset:160
	s_waitcnt lgkmcnt(2)
	v_mfma_f32_32x32x16_bf16 v[64:79], v[136:139], v[124:127], v[64:79]
	s_waitcnt lgkmcnt(1)
	v_mfma_f32_32x32x16_bf16 v[80:95], v[128:131], v[96:99], v[80:95]
	ds_read_b128 v[128:131], v140 offset:8832
	ds_read_b128 v[136:139], v140 offset:8864
	s_waitcnt lgkmcnt(1)
	v_mfma_f32_32x32x16_bf16 v[64:79], v[128:131], v[96:99], v[64:79]
	ds_read_b128 v[128:131], v140 offset:192
	ds_read_b128 v[206:209], v140 offset:224
	v_mfma_f32_32x32x16_bf16 v[80:95], v[132:135], v[104:107], v[80:95]
	s_waitcnt lgkmcnt(2)
	v_mfma_f32_32x32x16_bf16 v[64:79], v[136:139], v[104:107], v[64:79]
	s_waitcnt lgkmcnt(1)
	v_mfma_f32_32x32x16_bf16 v[80:95], v[128:131], v[112:115], v[80:95]
	ds_read_b128 v[128:131], v140 offset:8896
	ds_read_b128 v[132:135], v140 offset:8928
	s_waitcnt lgkmcnt(1)
	v_mfma_f32_32x32x16_bf16 v[64:79], v[128:131], v[112:115], v[64:79]
	v_lshl_add_u64 v[128:129], s[68:69], 0, v[182:183]
	v_lshl_add_u64 v[130:131], s[68:69], 0, v[180:181]
	global_load_dwordx4 v[140:143], v[128:129], off
	global_load_dwordx4 v[136:139], v[130:131], off
	v_lshl_add_u64 v[128:129], s[68:69], 0, v[176:177]
	v_lshl_add_u64 v[130:131], s[68:69], 0, v[178:179]
	s_waitcnt lgkmcnt(0)
	v_mfma_f32_32x32x16_bf16 v[64:79], v[132:135], v[120:123], v[64:79]
	global_load_dwordx4 v[132:135], v[128:129], off
	s_nop 0
	global_load_dwordx4 v[128:131], v[130:131], off
	v_mfma_f32_32x32x16_bf16 v[80:95], v[206:209], v[120:123], v[80:95]
	s_nop 7
	v_max3_f32 v185, v64, v65, v66
	v_max3_f32 v186, v67, v68, v69
	v_max3_f32 v206, v70, v71, v72
	v_max3_f32 v207, v73, v74, v75
	v_max3_f32 v185, v185, v76, v77
	v_max3_f32 v186, v186, v78, v79
	v_max3_f32 v206, v206, v80, v81
	v_max3_f32 v207, v207, v82, v83
	v_max3_f32 v185, v185, v84, v85
	v_max3_f32 v186, v186, v86, v87
	v_max3_f32 v206, v206, v88, v89
	v_max3_f32 v207, v207, v90, v91
	v_max3_f32 v185, v185, v92, v93
	v_max3_f32 v186, v186, v94, v95
	v_max3_f32 v185, v185, v186, v206
	v_max_f32_e32 v185, v185, v207
	v_mov_b32_e32 v186, v185
	s_nop 1
	v_permlane32_swap_b32_e32 v185, v186
	v_max_f32_e32 v186, v186, v186
	v_max_f32_e32 v185, v185, v185
	v_max_f32_e32 v205, v185, v186
	v_add_f32_e32 v185, 0x41000000, v184
	v_cmp_gt_f32_e32 vcc, v205, v185
	s_cbranch_vccz .LBB0_3393
	v_max_f32_e32 v185, v205, v205
	v_max_f32_e32 v186, v184, v184
	v_max_f32_e32 v185, v186, v185
	v_sub_f32_e32 v184, v184, v185
	v_exp_f32_e32 v184, v184
	s_nop 0
	v_pk_mul_f32 v[62:63], v[62:63], v[184:185] op_sel_hi:[1,0]
	v_pk_mul_f32 v[60:61], v[60:61], v[184:185] op_sel_hi:[1,0]
	v_pk_mul_f32 v[58:59], v[58:59], v[184:185] op_sel_hi:[1,0]
	v_pk_mul_f32 v[56:57], v[56:57], v[184:185] op_sel_hi:[1,0]
	v_pk_mul_f32 v[54:55], v[54:55], v[184:185] op_sel_hi:[1,0]
	v_pk_mul_f32 v[52:53], v[52:53], v[184:185] op_sel_hi:[1,0]
	v_pk_mul_f32 v[50:51], v[50:51], v[184:185] op_sel_hi:[1,0]
	v_pk_mul_f32 v[48:49], v[48:49], v[184:185] op_sel_hi:[1,0]
	v_pk_mul_f32 v[46:47], v[46:47], v[184:185] op_sel_hi:[1,0]
	v_pk_mul_f32 v[44:45], v[44:45], v[184:185] op_sel_hi:[1,0]
	v_pk_mul_f32 v[42:43], v[42:43], v[184:185] op_sel_hi:[1,0]
	v_pk_mul_f32 v[40:41], v[40:41], v[184:185] op_sel_hi:[1,0]
	v_pk_mul_f32 v[38:39], v[38:39], v[184:185] op_sel_hi:[1,0]
	v_pk_mul_f32 v[36:37], v[36:37], v[184:185] op_sel_hi:[1,0]
	v_pk_mul_f32 v[34:35], v[34:35], v[184:185] op_sel_hi:[1,0]
	v_pk_mul_f32 v[32:33], v[32:33], v[184:185] op_sel_hi:[1,0]
	v_pk_mul_f32 v[30:31], v[30:31], v[184:185] op_sel_hi:[1,0]
	v_pk_mul_f32 v[28:29], v[28:29], v[184:185] op_sel_hi:[1,0]
	v_pk_mul_f32 v[26:27], v[26:27], v[184:185] op_sel_hi:[1,0]
	v_pk_mul_f32 v[24:25], v[24:25], v[184:185] op_sel_hi:[1,0]
	v_pk_mul_f32 v[22:23], v[22:23], v[184:185] op_sel_hi:[1,0]
	v_pk_mul_f32 v[20:21], v[20:21], v[184:185] op_sel_hi:[1,0]
	v_pk_mul_f32 v[18:19], v[18:19], v[184:185] op_sel_hi:[1,0]
	v_pk_mul_f32 v[16:17], v[16:17], v[184:185] op_sel_hi:[1,0]
	v_pk_mul_f32 v[14:15], v[14:15], v[184:185] op_sel_hi:[1,0]
	v_pk_mul_f32 v[12:13], v[12:13], v[184:185] op_sel_hi:[1,0]
	v_pk_mul_f32 v[10:11], v[10:11], v[184:185] op_sel_hi:[1,0]
	v_pk_mul_f32 v[8:9], v[8:9], v[184:185] op_sel_hi:[1,0]
	v_pk_mul_f32 v[6:7], v[6:7], v[184:185] op_sel_hi:[1,0]
	v_pk_mul_f32 v[4:5], v[4:5], v[184:185] op_sel_hi:[1,0]
	v_pk_mul_f32 v[2:3], v[2:3], v[184:185] op_sel_hi:[1,0]
	v_pk_mul_f32 v[0:1], v[0:1], v[184:185] op_sel_hi:[1,0]
	v_mul_f32_e32 v204, v204, v184
	v_mov_b32_e32 v184, v185
	s_branch .LBB0_3393
